# also hoist the 64 serialized norm-scale loads in the P7-idle in-proj weight transposes (layer-1 weights)
# speedup vs baseline: 1.0086x; 1.0086x over previous
.LBB0_1635:
	s_or_b64 exec, exec, s[0:1]
	v_max_i32_e32 v0, 0, v0
	v_lshl_add_u64 v[12:13], v[0:1], 2, s[26:27]
	s_lshl_b32 s0, s10, 6
	v_mad_i64_i32 v[12:13], s[4:5], s0, v227, v[12:13]
	v_add_co_u32_e32 v14, vcc, 0xc000, v12
	s_mov_b32 s4, 0x86000
	s_nop 0
	v_addc_co_u32_e32 v15, vcc, 0, v13, vcc
	global_load_dword v85, v[14:15], off offset:1088
	v_add_co_u32_e32 v14, vcc, s9, v12
	global_load_dword v86, v[12:13], off
	s_nop 0
	v_addc_co_u32_e32 v15, vcc, 0, v13, vcc
	global_load_dword v84, v[14:15], off offset:2176
	v_add_co_u32_e32 v14, vcc, 0x24000, v12
	v_cmp_lt_i32_e64 s[40:41], -1, v66
	s_nop 0
	v_addc_co_u32_e32 v15, vcc, 0, v13, vcc
	global_load_dword v83, v[14:15], off offset:3264
	v_add_co_u32_e32 v14, vcc, 0x31000, v12
	v_cmp_ne_u32_e64 s[42:43], 1, v223
	s_nop 0
	v_addc_co_u32_e32 v15, vcc, 0, v13, vcc
	global_load_dword v82, v[14:15], off offset:256
	v_add_co_u32_e32 v14, vcc, 0x3d000, v12
	s_ashr_i32 s1, s0, 31
	s_nop 0
	v_addc_co_u32_e32 v15, vcc, 0, v13, vcc
	global_load_dword v80, v[14:15], off offset:1344
	v_add_co_u32_e32 v14, vcc, 0x49000, v12
	s_nop 1
	v_addc_co_u32_e32 v15, vcc, 0, v13, vcc
	global_load_dword v78, v[14:15], off offset:2432
	v_add_co_u32_e32 v14, vcc, 0x55000, v12
	s_nop 1
	v_addc_co_u32_e32 v15, vcc, 0, v13, vcc
	global_load_dword v81, v[14:15], off offset:3520
	v_add_co_u32_e32 v14, vcc, s21, v12
	s_nop 1
	v_addc_co_u32_e32 v15, vcc, 0, v13, vcc
	global_load_dword v79, v[14:15], off offset:512
	v_add_co_u32_e32 v14, vcc, s16, v12
	s_nop 1
	v_addc_co_u32_e32 v15, vcc, 0, v13, vcc
	global_load_dword v77, v[14:15], off offset:1600
	v_add_co_u32_e32 v14, vcc, s89, v12
	s_nop 1
	v_addc_co_u32_e32 v15, vcc, 0, v13, vcc
	global_load_dword v76, v[14:15], off offset:2688
	v_add_co_u32_e32 v14, vcc, s4, v12
	s_mov_b32 s4, 0x93000
	s_nop 0
	v_addc_co_u32_e32 v15, vcc, 0, v13, vcc
	global_load_dword v75, v[14:15], off offset:3776
	v_add_co_u32_e32 v14, vcc, s4, v12
	s_mov_b32 s4, 0x9f000
	s_nop 0
	v_addc_co_u32_e32 v15, vcc, 0, v13, vcc
	global_load_dword v74, v[14:15], off offset:768
	v_add_co_u32_e32 v14, vcc, s4, v12
	s_mov_b32 s4, 0xab000
	s_nop 0
	v_addc_co_u32_e32 v15, vcc, 0, v13, vcc
	global_load_dword v72, v[14:15], off offset:1856
	v_add_co_u32_e32 v14, vcc, s4, v12
	s_mov_b32 s4, 0xb7000
	s_nop 0
	v_addc_co_u32_e32 v15, vcc, 0, v13, vcc
	global_load_dword v70, v[14:15], off offset:2944
	v_add_co_u32_e32 v14, vcc, s4, v12
	s_mov_b32 s4, 0xc4000
	s_nop 0
	v_addc_co_u32_e32 v15, vcc, 0, v13, vcc
	global_load_dword v73, v[14:15], off offset:4032
	v_add_co_u32_e32 v14, vcc, s4, v12
	s_mov_b32 s4, 0xd0000
	s_nop 0
	v_addc_co_u32_e32 v15, vcc, 0, v13, vcc
	global_load_dword v71, v[14:15], off offset:1024
	v_add_co_u32_e32 v14, vcc, s4, v12
	s_mov_b32 s4, 0xdc000
	s_nop 0
	v_addc_co_u32_e32 v15, vcc, 0, v13, vcc
	global_load_dword v69, v[14:15], off offset:2112
	v_add_co_u32_e32 v14, vcc, s4, v12
	s_mov_b32 s4, 0xe9000
	s_nop 0
	v_addc_co_u32_e32 v15, vcc, 0, v13, vcc
	global_load_dword v68, v[14:15], off offset:3200
	v_add_co_u32_e32 v14, vcc, s4, v12
	s_mov_b32 s4, 0xf5000
	s_nop 0
	v_addc_co_u32_e32 v15, vcc, 0, v13, vcc
	global_load_dword v67, v[14:15], off offset:192
	v_add_co_u32_e32 v14, vcc, s4, v12
	s_mov_b32 s4, 0x101000
	s_nop 0
	v_addc_co_u32_e32 v15, vcc, 0, v13, vcc
	global_load_dword v65, v[14:15], off offset:1280
	v_add_co_u32_e32 v14, vcc, s4, v12
	s_mov_b32 s4, 0x10d000
	s_nop 0
	v_addc_co_u32_e32 v15, vcc, 0, v13, vcc
	global_load_dword v63, v[14:15], off offset:2368
	v_add_co_u32_e32 v14, vcc, s4, v12
	s_mov_b32 s4, 0x11a000
	s_nop 0
	v_addc_co_u32_e32 v15, vcc, 0, v13, vcc
	global_load_dword v61, v[14:15], off offset:3456
	v_add_co_u32_e32 v14, vcc, s4, v12
	s_mov_b32 s4, 0x126000
	s_nop 0
	v_addc_co_u32_e32 v15, vcc, 0, v13, vcc
	global_load_dword v64, v[14:15], off offset:448
	v_add_co_u32_e32 v14, vcc, s4, v12
	s_mov_b32 s4, 0x132000
	s_nop 0
	v_addc_co_u32_e32 v15, vcc, 0, v13, vcc
	global_load_dword v62, v[14:15], off offset:1536
	v_add_co_u32_e32 v14, vcc, s4, v12
	s_mov_b32 s4, 0x13e000
	s_nop 0
	v_addc_co_u32_e32 v15, vcc, 0, v13, vcc
	global_load_dword v60, v[14:15], off offset:2624
	v_add_co_u32_e32 v14, vcc, s4, v12
	s_mov_b32 s4, 0x14b000
	s_nop 0
	v_addc_co_u32_e32 v15, vcc, 0, v13, vcc
	global_load_dword v59, v[14:15], off offset:3712
	v_add_co_u32_e32 v14, vcc, s4, v12
	s_mov_b32 s4, 0x157000
	s_nop 0
	v_addc_co_u32_e32 v15, vcc, 0, v13, vcc
	global_load_dword v58, v[14:15], off offset:704
	v_add_co_u32_e32 v14, vcc, s4, v12
	s_mov_b32 s4, 0x163000
	s_nop 0
	v_addc_co_u32_e32 v15, vcc, 0, v13, vcc
	global_load_dword v57, v[14:15], off offset:1792
	v_add_co_u32_e32 v14, vcc, s4, v12
	s_mov_b32 s4, 0x16f000
	s_nop 0
	v_addc_co_u32_e32 v15, vcc, 0, v13, vcc
	global_load_dword v44, v[14:15], off offset:2880
	v_add_co_u32_e32 v14, vcc, s4, v12
	s_mov_b32 s4, 0x17c000
	s_nop 0
	v_addc_co_u32_e32 v15, vcc, 0, v13, vcc
	global_load_dword v42, v[14:15], off offset:3968
	v_add_co_u32_e32 v14, vcc, s4, v12
	s_mov_b32 s4, 0x188000
	s_nop 0
	v_addc_co_u32_e32 v15, vcc, 0, v13, vcc
	global_load_dword v45, v[14:15], off offset:960
	v_add_co_u32_e32 v14, vcc, s4, v12
	s_mov_b32 s4, 0x194000
	s_nop 0
	v_addc_co_u32_e32 v15, vcc, 0, v13, vcc
	global_load_dword v43, v[14:15], off offset:2048
	v_add_co_u32_e32 v14, vcc, s4, v12
	s_mov_b32 s4, 0x1a1000
	s_nop 0
	v_addc_co_u32_e32 v15, vcc, 0, v13, vcc
	global_load_dword v41, v[14:15], off offset:3136
	v_add_co_u32_e32 v14, vcc, s4, v12
	s_mov_b32 s4, 0x1ad000
	s_nop 0
	v_addc_co_u32_e32 v15, vcc, 0, v13, vcc
	global_load_dword v40, v[14:15], off offset:128
	v_add_co_u32_e32 v14, vcc, s4, v12
	s_mov_b32 s4, 0x1b9000
	s_nop 0
	v_addc_co_u32_e32 v15, vcc, 0, v13, vcc
	global_load_dword v39, v[14:15], off offset:1216
	v_add_co_u32_e32 v14, vcc, s4, v12
	s_mov_b32 s4, 0x1c5000
	s_nop 0
	v_addc_co_u32_e32 v15, vcc, 0, v13, vcc
	global_load_dword v38, v[14:15], off offset:2304
	v_add_co_u32_e32 v14, vcc, s4, v12
	s_mov_b32 s4, 0x1d2000
	s_nop 0
	v_addc_co_u32_e32 v15, vcc, 0, v13, vcc
	global_load_dword v36, v[14:15], off offset:3392
	v_add_co_u32_e32 v14, vcc, s4, v12
	s_mov_b32 s4, 0x1de000
	s_nop 0
	v_addc_co_u32_e32 v15, vcc, 0, v13, vcc
	global_load_dword v34, v[14:15], off offset:384
	v_add_co_u32_e32 v14, vcc, s4, v12
	s_mov_b32 s4, 0x1ea000
	s_nop 0
	v_addc_co_u32_e32 v15, vcc, 0, v13, vcc
	global_load_dword v37, v[14:15], off offset:1472
	v_add_co_u32_e32 v14, vcc, s4, v12
	s_mov_b32 s4, 0x1f6000
	s_nop 0
	v_addc_co_u32_e32 v15, vcc, 0, v13, vcc
	global_load_dword v35, v[14:15], off offset:2560
	v_add_co_u32_e32 v14, vcc, s4, v12
	s_mov_b32 s4, 0x203000
	s_nop 0
	v_addc_co_u32_e32 v15, vcc, 0, v13, vcc
	global_load_dword v33, v[14:15], off offset:3648
	v_add_co_u32_e32 v14, vcc, s4, v12
	s_mov_b32 s4, 0x20f000
	s_nop 0
	v_addc_co_u32_e32 v15, vcc, 0, v13, vcc
	global_load_dword v32, v[14:15], off offset:640
	v_add_co_u32_e32 v14, vcc, s4, v12
	s_mov_b32 s4, 0x21b000
	s_nop 0
	v_addc_co_u32_e32 v15, vcc, 0, v13, vcc
	global_load_dword v31, v[14:15], off offset:1728
	v_add_co_u32_e32 v14, vcc, s4, v12
	s_mov_b32 s4, 0x227000
	s_nop 0
	v_addc_co_u32_e32 v15, vcc, 0, v13, vcc
	global_load_dword v30, v[14:15], off offset:2816
	v_add_co_u32_e32 v14, vcc, s4, v12
	s_mov_b32 s4, 0x234000
	s_nop 0
	v_addc_co_u32_e32 v15, vcc, 0, v13, vcc
	global_load_dword v28, v[14:15], off offset:3904
	v_add_co_u32_e32 v14, vcc, s4, v12
	s_mov_b32 s4, 0x240000
	s_nop 0
	v_addc_co_u32_e32 v15, vcc, 0, v13, vcc
	global_load_dword v26, v[14:15], off offset:896
	v_add_co_u32_e32 v14, vcc, s4, v12
	s_mov_b32 s4, 0x24c000
	s_nop 0
	v_addc_co_u32_e32 v15, vcc, 0, v13, vcc
	global_load_dword v29, v[14:15], off offset:1984
	v_add_co_u32_e32 v14, vcc, s4, v12
	s_mov_b32 s4, 0x259000
	s_nop 0
	v_addc_co_u32_e32 v15, vcc, 0, v13, vcc
	global_load_dword v27, v[14:15], off offset:3072
	v_add_co_u32_e32 v14, vcc, s4, v12
	s_mov_b32 s4, 0x265000
	s_nop 0
	v_addc_co_u32_e32 v15, vcc, 0, v13, vcc
	global_load_dword v25, v[14:15], off offset:64
	v_add_co_u32_e32 v14, vcc, s4, v12
	s_mov_b32 s4, 0x271000
	s_nop 0
	v_addc_co_u32_e32 v15, vcc, 0, v13, vcc
	global_load_dword v24, v[14:15], off offset:1152
	v_add_co_u32_e32 v14, vcc, s4, v12
	s_mov_b32 s4, 0x27d000
	s_nop 0
	v_addc_co_u32_e32 v15, vcc, 0, v13, vcc
	global_load_dword v23, v[14:15], off offset:2240
	v_add_co_u32_e32 v14, vcc, s4, v12
	s_mov_b32 s4, 0x28a000
	s_nop 0
	v_addc_co_u32_e32 v15, vcc, 0, v13, vcc
	global_load_dword v22, v[14:15], off offset:3328
	v_add_co_u32_e32 v14, vcc, s4, v12
	s_mov_b32 s4, 0x296000
	s_nop 0
	v_addc_co_u32_e32 v15, vcc, 0, v13, vcc
	global_load_dword v20, v[14:15], off offset:320
	v_add_co_u32_e32 v14, vcc, s4, v12
	s_mov_b32 s4, 0x2a2000
	s_nop 0
	v_addc_co_u32_e32 v15, vcc, 0, v13, vcc
	global_load_dword v18, v[14:15], off offset:1408
	v_add_co_u32_e32 v14, vcc, s4, v12
	s_mov_b32 s4, 0x2ae000
	s_nop 0
	v_addc_co_u32_e32 v15, vcc, 0, v13, vcc
	global_load_dword v21, v[14:15], off offset:2496
	v_add_co_u32_e32 v14, vcc, s4, v12
	s_mov_b32 s4, 0x2bb000
	s_nop 0
	v_addc_co_u32_e32 v15, vcc, 0, v13, vcc
	global_load_dword v19, v[14:15], off offset:3584
	v_add_co_u32_e32 v14, vcc, s4, v12
	s_mov_b32 s4, 0x2c7000
	s_nop 0
	v_addc_co_u32_e32 v15, vcc, 0, v13, vcc
	global_load_dword v17, v[14:15], off offset:576
	v_add_co_u32_e32 v14, vcc, s4, v12
	s_mov_b32 s4, 0x2d3000
	s_nop 0
	v_addc_co_u32_e32 v15, vcc, 0, v13, vcc
	global_load_dword v16, v[14:15], off offset:1664
	v_add_co_u32_e32 v14, vcc, s4, v12
	s_mov_b32 s4, 0x2df000
	s_nop 0
	v_addc_co_u32_e32 v15, vcc, 0, v13, vcc
	v_add_co_u32_e32 v88, vcc, s4, v12
	global_load_dword v15, v[14:15], off offset:2752
	s_nop 0
	v_addc_co_u32_e32 v89, vcc, 0, v13, vcc
	global_load_dword v14, v[88:89], off offset:3840
	v_add_co_u32_e32 v88, vcc, 0x2ec000, v12
	s_nop 1
	v_addc_co_u32_e32 v89, vcc, 0, v13, vcc
	global_load_dword v11, v[88:89], off offset:832
	v_add_co_u32_e32 v88, vcc, 0x2f8000, v12
	s_nop 1
	v_addc_co_u32_e32 v89, vcc, 0, v13, vcc
	v_add_co_u32_e32 v12, vcc, 0x304000, v12
	global_load_dword v0, v[88:89], off offset:1920
	s_nop 0
	v_addc_co_u32_e32 v13, vcc, 0, v13, vcc
	global_load_dword v12, v[12:13], off offset:3008
	s_and_b64 vcc, exec, s[42:43]
	s_cbranch_vccnz .Lwjc_noscale
	s_lshl_b64 s[4:5], s[0:1], 2
	s_add_u32 s4, s37, s4
	s_addc_u32 s5, s33, s5
	v_lshlrev_b32_e32 v101, 2, v46
	global_load_dword v100, v101, s[4:5]
.Lwjc_noscale:
	s_waitcnt vmcnt(0)
	v_cndmask_b32_e64 v13, 0, v86, s[40:41]
	s_and_b64 vcc, exec, s[42:43]
	s_cbranch_vccnz .LBB0_1637
	v_readlane_b32 s4, v100, 0
	s_nop 1
	v_mul_f32_e32 v13, s4, v13
.LBB0_1637:
	ds_write_b32 v47, v13
	s_and_b64 vcc, exec, s[42:43]
	v_cndmask_b32_e64 v13, 0, v85, s[40:41]
	s_cbranch_vccnz .LBB0_1639
	v_readlane_b32 s4, v100, 1
	s_nop 1
	v_mul_f32_e32 v13, s4, v13
.LBB0_1639:
	ds_write_b32 v47, v13 offset:260
	s_and_b64 vcc, exec, s[42:43]
	v_cndmask_b32_e64 v13, 0, v84, s[40:41]
	s_cbranch_vccnz .LBB0_1641
	v_readlane_b32 s4, v100, 2
	s_nop 1
	v_mul_f32_e32 v13, s4, v13
.LBB0_1641:
	ds_write_b32 v47, v13 offset:520
	s_and_b64 vcc, exec, s[42:43]
	v_cndmask_b32_e64 v13, 0, v83, s[40:41]
	s_cbranch_vccnz .LBB0_1643
	v_readlane_b32 s4, v100, 3
	s_nop 1
	v_mul_f32_e32 v13, s4, v13
.LBB0_1643:
	ds_write_b32 v47, v13 offset:780
	s_and_b64 vcc, exec, s[42:43]
	v_cndmask_b32_e64 v13, 0, v82, s[40:41]
	s_cbranch_vccnz .LBB0_1645
	v_readlane_b32 s4, v100, 4
	s_nop 1
	v_mul_f32_e32 v13, s4, v13
.LBB0_1645:
	ds_write_b32 v47, v13 offset:1040
	s_and_b64 vcc, exec, s[42:43]
	v_cndmask_b32_e64 v13, 0, v80, s[40:41]
	s_cbranch_vccnz .LBB0_1647
	v_readlane_b32 s4, v100, 5
	s_nop 1
	v_mul_f32_e32 v13, s4, v13
.LBB0_1647:
	ds_write_b32 v47, v13 offset:1300
	s_and_b64 vcc, exec, s[42:43]
	v_cndmask_b32_e64 v13, 0, v78, s[40:41]
	s_cbranch_vccnz .LBB0_1649
	v_readlane_b32 s4, v100, 6
	s_nop 1
	v_mul_f32_e32 v13, s4, v13
.LBB0_1649:
	ds_write_b32 v47, v13 offset:1560
	s_and_b64 vcc, exec, s[42:43]
	v_cndmask_b32_e64 v13, 0, v81, s[40:41]
	s_cbranch_vccnz .LBB0_1651
	v_readlane_b32 s4, v100, 7
	s_nop 1
	v_mul_f32_e32 v13, s4, v13
.LBB0_1651:
	ds_write_b32 v47, v13 offset:1820
	s_and_b64 vcc, exec, s[42:43]
	v_cndmask_b32_e64 v13, 0, v79, s[40:41]
	s_cbranch_vccnz .LBB0_1653
	v_readlane_b32 s4, v100, 8
	s_nop 1
	v_mul_f32_e32 v13, s4, v13
.LBB0_1653:
	ds_write_b32 v47, v13 offset:2080
	s_and_b64 vcc, exec, s[42:43]
	v_cndmask_b32_e64 v13, 0, v77, s[40:41]
	s_cbranch_vccnz .LBB0_1655
	v_readlane_b32 s4, v100, 9
	s_nop 1
	v_mul_f32_e32 v13, s4, v13
.LBB0_1655:
	ds_write_b32 v47, v13 offset:2340
	s_and_b64 vcc, exec, s[42:43]
	v_cndmask_b32_e64 v13, 0, v76, s[40:41]
	s_cbranch_vccnz .LBB0_1657
	v_readlane_b32 s4, v100, 10
	s_nop 1
	v_mul_f32_e32 v13, s4, v13
.LBB0_1657:
	ds_write_b32 v47, v13 offset:2600
	s_and_b64 vcc, exec, s[42:43]
	v_cndmask_b32_e64 v13, 0, v75, s[40:41]
	s_cbranch_vccnz .LBB0_1659
	v_readlane_b32 s4, v100, 11
	s_nop 1
	v_mul_f32_e32 v13, s4, v13
.LBB0_1659:
	ds_write_b32 v47, v13 offset:2860
	s_and_b64 vcc, exec, s[42:43]
	v_cndmask_b32_e64 v13, 0, v74, s[40:41]
	s_cbranch_vccnz .LBB0_1661
	v_readlane_b32 s4, v100, 12
	s_nop 1
	v_mul_f32_e32 v13, s4, v13
.LBB0_1661:
	ds_write_b32 v47, v13 offset:3120
	s_and_b64 vcc, exec, s[42:43]
	v_cndmask_b32_e64 v13, 0, v72, s[40:41]
	s_cbranch_vccnz .LBB0_1663
	v_readlane_b32 s4, v100, 13
	s_nop 1
	v_mul_f32_e32 v13, s4, v13
.LBB0_1663:
	ds_write_b32 v47, v13 offset:3380
	s_and_b64 vcc, exec, s[42:43]
	v_cndmask_b32_e64 v13, 0, v70, s[40:41]
	s_cbranch_vccnz .LBB0_1665
	v_readlane_b32 s4, v100, 14
	s_nop 1
	v_mul_f32_e32 v13, s4, v13
.LBB0_1665:
	ds_write_b32 v47, v13 offset:3640
	s_and_b64 vcc, exec, s[42:43]
	v_cndmask_b32_e64 v13, 0, v73, s[40:41]
	s_cbranch_vccnz .LBB0_1667
	v_readlane_b32 s4, v100, 15
	s_nop 1
	v_mul_f32_e32 v13, s4, v13
.LBB0_1667:
	ds_write_b32 v47, v13 offset:3900
	s_and_b64 vcc, exec, s[42:43]
	v_cndmask_b32_e64 v13, 0, v71, s[40:41]
	s_cbranch_vccnz .LBB0_1669
	v_readlane_b32 s4, v100, 16
	s_nop 1
	v_mul_f32_e32 v13, s4, v13
.LBB0_1669:
	ds_write_b32 v47, v13 offset:4160
	s_and_b64 vcc, exec, s[42:43]
	v_cndmask_b32_e64 v13, 0, v69, s[40:41]
	s_cbranch_vccnz .LBB0_1671
	v_readlane_b32 s4, v100, 17
	s_nop 1
	v_mul_f32_e32 v13, s4, v13
.LBB0_1671:
	ds_write_b32 v47, v13 offset:4420
	s_and_b64 vcc, exec, s[42:43]
	v_cndmask_b32_e64 v13, 0, v68, s[40:41]
	s_cbranch_vccnz .LBB0_1673
	v_readlane_b32 s4, v100, 18
	s_nop 1
	v_mul_f32_e32 v13, s4, v13
.LBB0_1673:
	ds_write_b32 v47, v13 offset:4680
	s_and_b64 vcc, exec, s[42:43]
	v_cndmask_b32_e64 v13, 0, v67, s[40:41]
	s_cbranch_vccnz .LBB0_1675
	v_readlane_b32 s4, v100, 19
	s_nop 1
	v_mul_f32_e32 v13, s4, v13
.LBB0_1675:
	ds_write_b32 v47, v13 offset:4940
	s_and_b64 vcc, exec, s[42:43]
	v_cndmask_b32_e64 v13, 0, v65, s[40:41]
	s_cbranch_vccnz .LBB0_1677
	v_readlane_b32 s4, v100, 20
	s_nop 1
	v_mul_f32_e32 v13, s4, v13
.LBB0_1677:
	ds_write_b32 v47, v13 offset:5200
	s_and_b64 vcc, exec, s[42:43]
	v_cndmask_b32_e64 v13, 0, v63, s[40:41]
	s_cbranch_vccnz .LBB0_1679
	v_readlane_b32 s4, v100, 21
	s_nop 1
	v_mul_f32_e32 v13, s4, v13
.LBB0_1679:
	ds_write_b32 v47, v13 offset:5460
	s_and_b64 vcc, exec, s[42:43]
	v_cndmask_b32_e64 v13, 0, v61, s[40:41]
	s_cbranch_vccnz .LBB0_1681
	v_readlane_b32 s4, v100, 22
	s_nop 1
	v_mul_f32_e32 v13, s4, v13
.LBB0_1681:
	ds_write_b32 v47, v13 offset:5720
	s_and_b64 vcc, exec, s[42:43]
	v_cndmask_b32_e64 v13, 0, v64, s[40:41]
	s_cbranch_vccnz .LBB0_1683
	v_readlane_b32 s4, v100, 23
	s_nop 1
	v_mul_f32_e32 v13, s4, v13
.LBB0_1683:
	ds_write_b32 v47, v13 offset:5980
	s_and_b64 vcc, exec, s[42:43]
	v_cndmask_b32_e64 v13, 0, v62, s[40:41]
	s_cbranch_vccnz .LBB0_1685
	v_readlane_b32 s4, v100, 24
	s_nop 1
	v_mul_f32_e32 v13, s4, v13
.LBB0_1685:
	ds_write_b32 v47, v13 offset:6240
	s_and_b64 vcc, exec, s[42:43]
	v_cndmask_b32_e64 v13, 0, v60, s[40:41]
	s_cbranch_vccnz .LBB0_1687
	v_readlane_b32 s4, v100, 25
	s_nop 1
	v_mul_f32_e32 v13, s4, v13
.LBB0_1687:
	ds_write_b32 v47, v13 offset:6500
	s_and_b64 vcc, exec, s[42:43]
	v_cndmask_b32_e64 v13, 0, v59, s[40:41]
	s_cbranch_vccnz .LBB0_1689
	v_readlane_b32 s4, v100, 26
	s_nop 1
	v_mul_f32_e32 v13, s4, v13
.LBB0_1689:
	ds_write_b32 v47, v13 offset:6760
	s_and_b64 vcc, exec, s[42:43]
	v_cndmask_b32_e64 v13, 0, v58, s[40:41]
	s_cbranch_vccnz .LBB0_1691
	v_readlane_b32 s4, v100, 27
	s_nop 1
	v_mul_f32_e32 v13, s4, v13
.LBB0_1691:
	ds_write_b32 v47, v13 offset:7020
	s_and_b64 vcc, exec, s[42:43]
	v_cndmask_b32_e64 v13, 0, v57, s[40:41]
	s_cbranch_vccnz .LBB0_1693
	v_readlane_b32 s4, v100, 28
	s_nop 1
	v_mul_f32_e32 v13, s4, v13
.LBB0_1693:
	ds_write_b32 v47, v13 offset:7280
	s_and_b64 vcc, exec, s[42:43]
	v_cndmask_b32_e64 v13, 0, v44, s[40:41]
	s_cbranch_vccnz .LBB0_1695
	v_readlane_b32 s4, v100, 29
	s_nop 1
	v_mul_f32_e32 v13, s4, v13
.LBB0_1695:
	ds_write_b32 v47, v13 offset:7540
	s_and_b64 vcc, exec, s[42:43]
	v_cndmask_b32_e64 v13, 0, v42, s[40:41]
	s_cbranch_vccnz .LBB0_1697
	v_readlane_b32 s4, v100, 30
	s_nop 1
	v_mul_f32_e32 v13, s4, v13
.LBB0_1697:
	ds_write_b32 v47, v13 offset:7800
	s_and_b64 vcc, exec, s[42:43]
	v_cndmask_b32_e64 v13, 0, v45, s[40:41]
	s_cbranch_vccnz .LBB0_1699
	v_readlane_b32 s4, v100, 31
	s_nop 1
	v_mul_f32_e32 v13, s4, v13
.LBB0_1699:
	ds_write_b32 v47, v13 offset:8060
	s_and_b64 vcc, exec, s[42:43]
	v_cndmask_b32_e64 v13, 0, v43, s[40:41]
	s_cbranch_vccnz .LBB0_1701
	v_readlane_b32 s4, v100, 32
	s_nop 1
	v_mul_f32_e32 v13, s4, v13
.LBB0_1701:
	ds_write_b32 v47, v13 offset:8320
	s_and_b64 vcc, exec, s[42:43]
	v_cndmask_b32_e64 v13, 0, v41, s[40:41]
	s_cbranch_vccnz .LBB0_1703
	v_readlane_b32 s4, v100, 33
	s_nop 1
	v_mul_f32_e32 v13, s4, v13
.LBB0_1703:
	ds_write_b32 v47, v13 offset:8580
	s_and_b64 vcc, exec, s[42:43]
	v_cndmask_b32_e64 v13, 0, v40, s[40:41]
	s_cbranch_vccnz .LBB0_1705
	v_readlane_b32 s4, v100, 34
	s_nop 1
	v_mul_f32_e32 v13, s4, v13
.LBB0_1705:
	ds_write_b32 v47, v13 offset:8840
	s_and_b64 vcc, exec, s[42:43]
	v_cndmask_b32_e64 v13, 0, v39, s[40:41]
	s_cbranch_vccnz .LBB0_1707
	v_readlane_b32 s4, v100, 35
	s_nop 1
	v_mul_f32_e32 v13, s4, v13
.LBB0_1707:
	ds_write_b32 v47, v13 offset:9100
	s_and_b64 vcc, exec, s[42:43]
	v_cndmask_b32_e64 v13, 0, v38, s[40:41]
	s_cbranch_vccnz .LBB0_1709
	v_readlane_b32 s4, v100, 36
	s_nop 1
	v_mul_f32_e32 v13, s4, v13
.LBB0_1709:
	ds_write_b32 v47, v13 offset:9360
	s_and_b64 vcc, exec, s[42:43]
	v_cndmask_b32_e64 v13, 0, v36, s[40:41]
	s_cbranch_vccnz .LBB0_1711
	v_readlane_b32 s4, v100, 37
	s_nop 1
	v_mul_f32_e32 v13, s4, v13
.LBB0_1711:
	ds_write_b32 v47, v13 offset:9620
	s_and_b64 vcc, exec, s[42:43]
	v_cndmask_b32_e64 v13, 0, v34, s[40:41]
	s_cbranch_vccnz .LBB0_1713
	v_readlane_b32 s4, v100, 38
	s_nop 1
	v_mul_f32_e32 v13, s4, v13
.LBB0_1713:
	ds_write_b32 v47, v13 offset:9880
	s_and_b64 vcc, exec, s[42:43]
	v_cndmask_b32_e64 v13, 0, v37, s[40:41]
	s_cbranch_vccnz .LBB0_1715
	v_readlane_b32 s4, v100, 39
	s_nop 1
	v_mul_f32_e32 v13, s4, v13
.LBB0_1715:
	ds_write_b32 v47, v13 offset:10140
	s_and_b64 vcc, exec, s[42:43]
	v_cndmask_b32_e64 v13, 0, v35, s[40:41]
	s_cbranch_vccnz .LBB0_1717
	v_readlane_b32 s4, v100, 40
	s_nop 1
	v_mul_f32_e32 v13, s4, v13
.LBB0_1717:
	ds_write_b32 v47, v13 offset:10400
	s_and_b64 vcc, exec, s[42:43]
	v_cndmask_b32_e64 v13, 0, v33, s[40:41]
	s_cbranch_vccnz .LBB0_1719
	v_readlane_b32 s4, v100, 41
	s_nop 1
	v_mul_f32_e32 v13, s4, v13
.LBB0_1719:
	ds_write_b32 v47, v13 offset:10660
	s_and_b64 vcc, exec, s[42:43]
	v_cndmask_b32_e64 v13, 0, v32, s[40:41]
	s_cbranch_vccnz .LBB0_1721
	v_readlane_b32 s4, v100, 42
	s_nop 1
	v_mul_f32_e32 v13, s4, v13
.LBB0_1721:
	ds_write_b32 v47, v13 offset:10920
	s_and_b64 vcc, exec, s[42:43]
	v_cndmask_b32_e64 v13, 0, v31, s[40:41]
	s_cbranch_vccnz .LBB0_1723
	v_readlane_b32 s4, v100, 43
	s_nop 1
	v_mul_f32_e32 v13, s4, v13
.LBB0_1723:
	ds_write_b32 v47, v13 offset:11180
	s_and_b64 vcc, exec, s[42:43]
	v_cndmask_b32_e64 v13, 0, v30, s[40:41]
	s_cbranch_vccnz .LBB0_1725
	v_readlane_b32 s4, v100, 44
	s_nop 1
	v_mul_f32_e32 v13, s4, v13
.LBB0_1725:
	ds_write_b32 v47, v13 offset:11440
	s_and_b64 vcc, exec, s[42:43]
	v_cndmask_b32_e64 v13, 0, v28, s[40:41]
	s_cbranch_vccnz .LBB0_1727
	v_readlane_b32 s4, v100, 45
	s_nop 1
	v_mul_f32_e32 v13, s4, v13
.LBB0_1727:
	ds_write_b32 v47, v13 offset:11700
	s_and_b64 vcc, exec, s[42:43]
	v_cndmask_b32_e64 v13, 0, v26, s[40:41]
	s_cbranch_vccnz .LBB0_1729
	v_readlane_b32 s4, v100, 46
	s_nop 1
	v_mul_f32_e32 v13, s4, v13
.LBB0_1729:
	ds_write_b32 v47, v13 offset:11960
	s_and_b64 vcc, exec, s[42:43]
	v_cndmask_b32_e64 v13, 0, v29, s[40:41]
	s_cbranch_vccnz .LBB0_1731
	v_readlane_b32 s4, v100, 47
	s_nop 1
	v_mul_f32_e32 v13, s4, v13
.LBB0_1731:
	ds_write_b32 v47, v13 offset:12220
	s_and_b64 vcc, exec, s[42:43]
	v_cndmask_b32_e64 v13, 0, v27, s[40:41]
	s_cbranch_vccnz .LBB0_1733
	v_readlane_b32 s4, v100, 48
	s_nop 1
	v_mul_f32_e32 v13, s4, v13
.LBB0_1733:
	ds_write_b32 v47, v13 offset:12480
	s_and_b64 vcc, exec, s[42:43]
	v_cndmask_b32_e64 v13, 0, v25, s[40:41]
	s_cbranch_vccnz .LBB0_1735
	v_readlane_b32 s4, v100, 49
	s_nop 1
	v_mul_f32_e32 v13, s4, v13
.LBB0_1735:
	ds_write_b32 v47, v13 offset:12740
	s_and_b64 vcc, exec, s[42:43]
	v_cndmask_b32_e64 v13, 0, v24, s[40:41]
	s_cbranch_vccnz .LBB0_1737
	v_readlane_b32 s4, v100, 50
	s_nop 1
	v_mul_f32_e32 v13, s4, v13
.LBB0_1737:
	ds_write_b32 v47, v13 offset:13000
	s_and_b64 vcc, exec, s[42:43]
	v_cndmask_b32_e64 v13, 0, v23, s[40:41]
	s_cbranch_vccnz .LBB0_1739
	v_readlane_b32 s4, v100, 51
	s_nop 1
	v_mul_f32_e32 v13, s4, v13
.LBB0_1739:
	ds_write_b32 v47, v13 offset:13260
	s_and_b64 vcc, exec, s[42:43]
	v_cndmask_b32_e64 v13, 0, v22, s[40:41]
	s_cbranch_vccnz .LBB0_1741
	v_readlane_b32 s4, v100, 52
	s_nop 1
	v_mul_f32_e32 v13, s4, v13
.LBB0_1741:
	ds_write_b32 v47, v13 offset:13520
	s_and_b64 vcc, exec, s[42:43]
	v_cndmask_b32_e64 v13, 0, v20, s[40:41]
	s_cbranch_vccnz .LBB0_1743
	v_readlane_b32 s4, v100, 53
	s_nop 1
	v_mul_f32_e32 v13, s4, v13
.LBB0_1743:
	ds_write_b32 v47, v13 offset:13780
	s_and_b64 vcc, exec, s[42:43]
	v_cndmask_b32_e64 v13, 0, v18, s[40:41]
	s_cbranch_vccnz .LBB0_1745
	v_readlane_b32 s4, v100, 54
	s_nop 1
	v_mul_f32_e32 v13, s4, v13
.LBB0_1745:
	ds_write_b32 v47, v13 offset:14040
	s_and_b64 vcc, exec, s[42:43]
	v_cndmask_b32_e64 v13, 0, v21, s[40:41]
	s_cbranch_vccnz .LBB0_1747
	v_readlane_b32 s4, v100, 55
	s_nop 1
	v_mul_f32_e32 v13, s4, v13
.LBB0_1747:
	ds_write_b32 v47, v13 offset:14300
	s_and_b64 vcc, exec, s[42:43]
	v_cndmask_b32_e64 v13, 0, v19, s[40:41]
	s_cbranch_vccnz .LBB0_1749
	v_readlane_b32 s4, v100, 56
	s_nop 1
	v_mul_f32_e32 v13, s4, v13
.LBB0_1749:
	ds_write_b32 v47, v13 offset:14560
	s_and_b64 vcc, exec, s[42:43]
	v_cndmask_b32_e64 v13, 0, v17, s[40:41]
	s_cbranch_vccnz .LBB0_1751
	v_readlane_b32 s4, v100, 57
	s_nop 1
	v_mul_f32_e32 v13, s4, v13
.LBB0_1751:
	ds_write_b32 v47, v13 offset:14820
	s_and_b64 vcc, exec, s[42:43]
	v_cndmask_b32_e64 v13, 0, v16, s[40:41]
	s_cbranch_vccnz .LBB0_1753
	v_readlane_b32 s4, v100, 58
	s_nop 1
	v_mul_f32_e32 v13, s4, v13
.LBB0_1753:
	ds_write_b32 v47, v13 offset:15080
	s_and_b64 vcc, exec, s[42:43]
	v_cndmask_b32_e64 v13, 0, v15, s[40:41]
	s_cbranch_vccnz .LBB0_1755
	v_readlane_b32 s4, v100, 59
	s_nop 1
	v_mul_f32_e32 v13, s4, v13
.LBB0_1755:
	ds_write_b32 v47, v13 offset:15340
	s_and_b64 vcc, exec, s[42:43]
	v_cndmask_b32_e64 v13, 0, v14, s[40:41]
	s_cbranch_vccnz .LBB0_1757
	v_readlane_b32 s4, v100, 60
	s_nop 1
	v_mul_f32_e32 v13, s4, v13
.LBB0_1757:
	s_and_b64 vcc, exec, s[42:43]
	v_cndmask_b32_e64 v11, 0, v11, s[40:41]
	ds_write_b32 v47, v13 offset:15600
	s_cbranch_vccnz .LBB0_1759
	v_readlane_b32 s4, v100, 61
	s_nop 1
	v_mul_f32_e32 v11, s4, v11
.LBB0_1759:
	s_and_b64 vcc, exec, s[42:43]
	v_cndmask_b32_e64 v0, 0, v0, s[40:41]
	ds_write_b32 v47, v11 offset:15860
	s_cbranch_vccnz .LBB0_1761
	v_readlane_b32 s4, v100, 62
	s_nop 1
	v_mul_f32_e32 v0, s4, v0
.LBB0_1761:
	ds_write_b32 v47, v0 offset:16120
	s_and_b64 vcc, exec, s[42:43]
	v_cndmask_b32_e64 v0, 0, v12, s[40:41]
	s_cbranch_vccnz .LBB0_1549
	v_readlane_b32 s4, v100, 63
	s_nop 1
	v_mul_f32_e32 v0, s4, v0
	s_branch .LBB0_1549
